# MLA softmax: row-max taken on raw scores and scaled once (monotonic, bit-identical), removes 30 v_mul per chunk per wave; on top of K-loop rebalanced version
# speedup vs baseline: 1.0021x; 1.0021x over previous
; DEV f32x4 mfma16(bf16x8 a, bf16x8 b, f32x4 c) { return __builtin_amdgcn_mfma_f32_16x16x32_bf16(a, b, c, 0, 0, 0); }
; template <int KS>
; DEV void attn_chunk(const unsigned char* Kl, const unsigned char* Vl, const bf16x8 (&qf)[2][KS], f32x4 (&O)[2][4], float (&mrun)[2], float (&lrun)[2],
;                     bool masked, int key0, int qw0, float sl2, int lane, int fr, int fq) {
;     ...
; #pragma unroll
;   for (int kt = 0; kt < 4; ++kt) {
;     sc[0][kt] = (f32x4){0.f, 0.f, 0.f, 0.f}; sc[1][kt] = (f32x4){0.f, 0.f, 0.f, 0.f};
; #pragma unroll
;     for (int kk = 0; kk < KS; ++kk) {
;       bf16x8 kf = *reinterpret_cast<const bf16x8*>(Kl + ((kt * 16 + fr) * KP + kk * 32 + fq * 8) * 2);
;       sc[0][kt] = mfma16(kf, qf[0][kk], sc[0][kt]); sc[1][kt] = mfma16(kf, qf[1][kk], sc[1][kt]);
;     }
;   }
;   bf16x8 pf[2][2];
; #pragma unroll
;   for (int qi = 0; qi < 2; ++qi) {
;     float mx = -1e30f;
; #pragma unroll
;     for (int kt = 0; kt < 4; ++kt)
; #pragma unroll
;       for (int r = 0; r < 4; ++r) { float v = sc[qi][kt][r] * sl2;
;         if (masked) { int kp = key0 + kt * 16 + fq * 4 + r; int dq = qw0 + qi * 16 + fr - kp; if (dq > 128 || dq < -128) v = -1e30f; }
;         sc[qi][kt][r] = v; mx = fmaxf(mx, v); }
;     mx = max_x16_x32(mx);
;     const float mnew = fmaxf(mrun[qi], mx);
;     const float alpha = __builtin_amdgcn_exp2f(mrun[qi] - mnew);
;     mrun[qi] = mnew;
;     float ps = 0.f;
; #pragma unroll
;     for (int kt = 0; kt < 4; ++kt)
; #pragma unroll
;       for (int r = 0; r < 4; ++r) { float pvv = __builtin_amdgcn_exp2f(sc[qi][kt][r] - mnew); ps += pvv; sc[qi][kt][r] = pvv; }
;     pf[qi][0] = pack8(sc[qi][0][0], sc[qi][0][1], sc[qi][0][2], sc[qi][0][3], sc[qi][1][0], sc[qi][1][1], sc[qi][1][2], sc[qi][1][3]);
;     pf[qi][1] = pack8(sc[qi][2][0], sc[qi][2][1], sc[qi][2][2], sc[qi][2][3], sc[qi][3][0], sc[qi][3][1], sc[qi][3][2], sc[qi][3][3]);
;     lrun[qi] = lrun[qi] * alpha + ps;
; #pragma unroll
;     for (int dt = 0; dt < 4; ++dt) O[qi][dt] *= alpha;
;   }
.LBB0_616:
	ds_read_b128 v[82:85], v202
	ds_read_b128 v[90:93], v202 offset:64
	s_mov_b32 s0, 0xf149f2ca
	s_mov_b32 s1, 0x3e16c740
	s_waitcnt lgkmcnt(1)
	v_mfma_f32_16x16x32_bf16 v[86:89], v[82:85], v[2:5], 0
	ds_read_b128 v[98:101], v202 offset:3392
	ds_read_b128 v[102:105], v202 offset:6720
	ds_read_b128 v[122:125], v202 offset:10048
	v_mfma_f32_16x16x32_bf16 v[82:85], v[82:85], v[18:21], 0
	s_waitcnt lgkmcnt(3)
	v_mfma_f32_16x16x32_bf16 v[86:89], v[90:93], v[6:9], v[86:89]
	v_mfma_f32_16x16x32_bf16 v[82:85], v[90:93], v[14:17], v[82:85]
	ds_read_b128 v[90:93], v202 offset:128
	s_waitcnt lgkmcnt(0)
	v_mfma_f32_16x16x32_bf16 v[86:89], v[90:93], v[10:13], v[86:89]
	v_mfma_f32_16x16x32_bf16 v[90:93], v[90:93], v[22:25], v[82:85]
	s_nop 3
	ds_read_b128 v[82:85], v202 offset:3328
	s_waitcnt lgkmcnt(0)
	v_mfma_f32_16x16x32_bf16 v[94:97], v[82:85], v[2:5], 0
	s_nop 0
	v_mfma_f32_16x16x32_bf16 v[82:85], v[82:85], v[18:21], 0
	v_mfma_f32_16x16x32_bf16 v[94:97], v[98:101], v[6:9], v[94:97]
	v_mfma_f32_16x16x32_bf16 v[82:85], v[98:101], v[14:17], v[82:85]
	ds_read_b128 v[98:101], v202 offset:3456
	s_waitcnt lgkmcnt(0)
	v_mfma_f32_16x16x32_bf16 v[132:135], v[98:101], v[10:13], v[94:97]
	v_mfma_f32_16x16x32_bf16 v[94:97], v[98:101], v[22:25], v[82:85]
	s_nop 3
	ds_read_b128 v[82:85], v202 offset:6656
	s_waitcnt lgkmcnt(0)
	v_mfma_f32_16x16x32_bf16 v[98:101], v[82:85], v[2:5], 0
	v_mfma_f32_16x16x32_bf16 v[82:85], v[82:85], v[18:21], 0
	v_mfma_f32_16x16x32_bf16 v[98:101], v[102:105], v[6:9], v[98:101]
	v_mfma_f32_16x16x32_bf16 v[82:85], v[102:105], v[14:17], v[82:85]
	ds_read_b128 v[102:105], v202 offset:6784
	s_waitcnt lgkmcnt(0)
	v_mfma_f32_16x16x32_bf16 v[140:143], v[102:105], v[10:13], v[98:101]
	v_mfma_f32_16x16x32_bf16 v[98:101], v[102:105], v[22:25], v[82:85]
	s_nop 3
	ds_read_b128 v[82:85], v202 offset:9984
	s_waitcnt lgkmcnt(0)
	v_mfma_f32_16x16x32_bf16 v[102:105], v[82:85], v[2:5], 0
	v_mfma_f32_16x16x32_bf16 v[82:85], v[82:85], v[18:21], 0
	v_mfma_f32_16x16x32_bf16 v[102:105], v[122:125], v[6:9], v[102:105]
	v_mfma_f32_16x16x32_bf16 v[82:85], v[122:125], v[14:17], v[82:85]
	ds_read_b128 v[122:125], v202 offset:10112
	s_waitcnt lgkmcnt(0)
	v_mfma_f32_16x16x32_bf16 v[148:151], v[122:125], v[10:13], v[102:105]
	v_mfma_f32_16x16x32_bf16 v[102:105], v[122:125], v[22:25], v[82:85]
	v_max3_f32 v123, v90, s0, v91
	s_nop 0
	s_nop 5
	v_max3_f32 v82, v86, s0, v87
	v_max3_f32 v82, v82, v88, v89
	v_max3_f32 v82, v82, v132, v133
	v_max3_f32 v82, v82, v134, v135
	v_max3_f32 v82, v82, v140, v141
	v_max3_f32 v82, v82, v142, v143
	v_max3_f32 v82, v82, v148, v149
	v_max3_f32 v82, v82, v150, v151
	v_mul_f32_e32 v82, 0x3e16c740, v82
	v_mov_b32_e32 v83, v82
	v_max3_f32 v123, v123, v92, v93
	s_nop 0
	v_permlane32_swap_b32_e32 v82, v83
	v_max3_f32 v123, v123, v94, v95
	v_max_f32_e32 v83, v83, v83
	v_max_f32_e32 v82, v82, v82
	v_max3_f32 v123, v123, v96, v97
	v_max_f32_e32 v82, v82, v83
	v_max3_f32 v123, v123, v98, v99
	v_mov_b32_e32 v83, v82
	v_max3_f32 v123, v123, v100, v101
	s_nop 0
	v_permlane16_swap_b32_e32 v82, v83
	v_max3_f32 v123, v123, v102, v103
	v_max3_f32 v156, v218, v82, v83
	v_max3_f32 v123, v123, v104, v105
	v_fma_f32 v83, v86, s1, -v156
	v_mul_f32_e32 v123, 0x3e16c740, v123
	v_mov_b32_e32 v125, v123
	v_exp_f32_e32 v122, v83
	v_fma_f32 v83, v87, s1, -v156
	v_permlane32_swap_b32_e32 v123, v125
	v_exp_f32_e32 v126, v83
	v_fma_f32 v83, v88, s1, -v156
	v_max_f32_e32 v125, v125, v125
	v_max_f32_e32 v123, v123, v123
	v_exp_f32_e32 v124, v83
	v_fma_f32 v83, v89, s1, -v156
	v_max_f32_e32 v123, v123, v125
	v_exp_f32_e32 v128, v83
	v_fma_f32 v83, v132, s1, -v156
	v_mov_b32_e32 v125, v123
	v_exp_f32_e32 v132, v83
	v_fma_f32 v83, v133, s1, -v156
	v_permlane16_swap_b32_e32 v123, v125
	v_exp_f32_e32 v130, v83
	v_fma_f32 v83, v134, s1, -v156
	v_max3_f32 v157, v219, v123, v125
	v_exp_f32_e32 v134, v83
	v_fma_f32 v83, v135, s1, -v156
	v_fma_f32 v90, v90, s1, -v157
	v_exp_f32_e32 v138, v83
	v_fma_f32 v83, v140, s1, -v156
	v_exp_f32_e32 v123, v90
	v_fma_f32 v90, v91, s1, -v157
	v_sub_f32_e32 v82, v218, v156
	v_exp_f32_e32 v136, v83
	v_fma_f32 v83, v141, s1, -v156
	v_exp_f32_e32 v127, v90
	v_fma_f32 v90, v92, s1, -v157
	v_exp_f32_e32 v140, v83
	v_fma_f32 v83, v142, s1, -v156
	v_exp_f32_e32 v142, v82
	v_exp_f32_e32 v125, v90
	v_fma_f32 v90, v93, s1, -v157
	v_exp_f32_e32 v129, v90
	v_fma_f32 v90, v94, s1, -v157
	v_exp_f32_e32 v133, v90
	v_fma_f32 v90, v95, s1, -v157
	v_exp_f32_e32 v131, v90
	v_fma_f32 v90, v96, s1, -v157
	v_exp_f32_e32 v146, v83
	v_fma_f32 v83, v143, s1, -v156
	v_pk_mul_f32 v[68:69], v[68:69], v[142:143] op_sel_hi:[1,0]
	v_pk_mul_f32 v[66:67], v[66:67], v[142:143] op_sel_hi:[1,0]
	v_pk_mul_f32 v[72:73], v[72:73], v[142:143] op_sel_hi:[1,0]
	v_pk_mul_f32 v[70:71], v[70:71], v[142:143] op_sel_hi:[1,0]
	v_pk_mul_f32 v[76:77], v[76:77], v[142:143] op_sel_hi:[1,0]
	v_pk_mul_f32 v[74:75], v[74:75], v[142:143] op_sel_hi:[1,0]
	v_pk_mul_f32 v[80:81], v[80:81], v[142:143] op_sel_hi:[1,0]
	v_pk_mul_f32 v[78:79], v[78:79], v[142:143] op_sel_hi:[1,0]
	v_sub_f32_e32 v143, v219, v157
	v_exp_f32_e32 v135, v90
	v_fma_f32 v90, v97, s1, -v157
	v_exp_f32_e32 v139, v90
	v_fma_f32 v90, v98, s1, -v157
	v_exp_f32_e32 v143, v143
	v_exp_f32_e32 v137, v90
	v_fma_f32 v90, v99, s1, -v157
	v_exp_f32_e32 v141, v90
	v_fma_f32 v90, v100, s1, -v157
	v_exp_f32_e32 v147, v90
	v_fma_f32 v90, v101, s1, -v157
	v_exp_f32_e32 v145, v90
	v_fma_f32 v90, v102, s1, -v157
	v_mov_b32_e32 v98, v143
	v_add_u32_e32 v102, 0x6800, v203
	v_pk_mul_f32 v[52:53], v[52:53], v[98:99] op_sel_hi:[1,0]
	v_pk_mul_f32 v[50:51], v[50:51], v[98:99] op_sel_hi:[1,0]
	v_pk_mul_f32 v[56:57], v[56:57], v[98:99] op_sel_hi:[1,0]
	v_pk_mul_f32 v[54:55], v[54:55], v[98:99] op_sel_hi:[1,0]
	v_pk_mul_f32 v[60:61], v[60:61], v[98:99] op_sel_hi:[1,0]
	v_pk_mul_f32 v[58:59], v[58:59], v[98:99] op_sel_hi:[1,0]
	v_pk_mul_f32 v[64:65], v[64:65], v[98:99] op_sel_hi:[1,0]
	v_pk_mul_f32 v[62:63], v[62:63], v[98:99] op_sel_hi:[1,0]
	ds_read2_b64 v[98:101], v102 offset1:4
	v_cvt_pk_bf16_f32 v86, v122, v126
	v_cvt_pk_bf16_f32 v87, v124, v128
	v_cvt_pk_bf16_f32 v88, v132, v130
	v_cvt_pk_bf16_f32 v89, v134, v138
	v_cvt_pk_bf16_f32 v94, v123, v127
	v_cvt_pk_bf16_f32 v95, v125, v129
	v_cvt_pk_bf16_f32 v96, v133, v131
	v_cvt_pk_bf16_f32 v97, v135, v139
	v_exp_f32_e32 v144, v83
	v_fma_f32 v83, v148, s1, -v156
	s_waitcnt lgkmcnt(0)
; DEV f32x4 mfma16(bf16x8 a, bf16x8 b, f32x4 c) { return __builtin_amdgcn_mfma_f32_16x16x32_bf16(a, b, c, 0, 0, 0); }
; template <int KS>
; DEV void attn_chunk(const unsigned char* Kl, const unsigned char* Vl, const bf16x8 (&qf)[2][KS], f32x4 (&O)[2][4], float (&mrun)[2], float (&lrun)[2],
;                     bool masked, int key0, int qw0, float sl2, int lane, int fr, int fq) {
;     ...
; #pragma unroll
;   for (int dt = 0; dt < 4; ++dt)
; #pragma unroll
;     for (int sub = 0; sub < 2; ++sub) {
;       const unsigned char* vp = Vl + ((dt * 16 + fr) * VP + sub * 32 + fq * 4) * 2;
;       u32x2 v0 = *reinterpret_cast<const u32x2*>(vp), v1 = *reinterpret_cast<const u32x2*>(vp + 32);
;       u32x4 vv = {v0[0], v0[1], v1[0], v1[1]};
;       bf16x8 vf = *reinterpret_cast<bf16x8*>(&vv);
;       O[0][dt] = mfma16(vf, pf[0][sub], O[0][dt]); O[1][dt] = mfma16(vf, pf[1][sub], O[1][dt]);
;     }
	v_mfma_f32_16x16x32_bf16 v[66:69], v[98:101], v[86:89], v[66:69]
	v_exp_f32_e32 v154, v83
	v_fma_f32 v83, v149, s1, -v156
	v_exp_f32_e32 v155, v90
	v_mfma_f32_16x16x32_bf16 v[50:53], v[98:101], v[94:97], v[50:53]
	ds_read2_b64 v[98:101], v102 offset0:8 offset1:12
	v_fma_f32 v90, v103, s1, -v157
	v_exp_f32_e32 v152, v83
	v_fma_f32 v83, v150, s1, -v156
	v_exp_f32_e32 v153, v90
	v_fma_f32 v90, v104, s1, -v157
	v_exp_f32_e32 v150, v83
	v_fma_f32 v83, v151, s1, -v156
	v_exp_f32_e32 v151, v90
	v_fma_f32 v90, v105, s1, -v157
	v_exp_f32_e32 v148, v83
	v_exp_f32_e32 v149, v90
	v_cvt_pk_bf16_f32 v82, v136, v140
	v_cvt_pk_bf16_f32 v83, v146, v144
	v_cvt_pk_bf16_f32 v84, v154, v152
	v_cvt_pk_bf16_f32 v85, v150, v148
	v_cvt_pk_bf16_f32 v90, v137, v141
	v_cvt_pk_bf16_f32 v91, v147, v145
	v_cvt_pk_bf16_f32 v92, v155, v153
	v_cvt_pk_bf16_f32 v93, v151, v149
	v_add_u32_e32 v102, 0x7000, v203
	s_waitcnt lgkmcnt(0)
	v_mfma_f32_16x16x32_bf16 v[66:69], v[98:101], v[82:85], v[66:69]
	v_mfma_f32_16x16x32_bf16 v[50:53], v[98:101], v[90:93], v[50:53]
	ds_read2_b64 v[98:101], v102 offset0:32 offset1:36
	s_waitcnt lgkmcnt(0)
	v_mfma_f32_16x16x32_bf16 v[70:73], v[98:101], v[86:89], v[70:73]
	v_mfma_f32_16x16x32_bf16 v[54:57], v[98:101], v[94:97], v[54:57]
	ds_read2_b64 v[98:101], v102 offset0:40 offset1:44
	v_add_u32_e32 v102, 0x7800, v203
	s_waitcnt lgkmcnt(0)
	v_mfma_f32_16x16x32_bf16 v[70:73], v[98:101], v[82:85], v[70:73]
	v_mfma_f32_16x16x32_bf16 v[54:57], v[98:101], v[90:93], v[54:57]
	ds_read2_b64 v[98:101], v102 offset0:64 offset1:68
	s_waitcnt lgkmcnt(0)
	v_mfma_f32_16x16x32_bf16 v[74:77], v[98:101], v[86:89], v[74:77]
	v_mfma_f32_16x16x32_bf16 v[58:61], v[98:101], v[94:97], v[58:61]
	ds_read2_b64 v[98:101], v102 offset0:72 offset1:76
	v_add_u32_e32 v102, 0x8000, v203
	s_waitcnt lgkmcnt(0)
	v_mfma_f32_16x16x32_bf16 v[74:77], v[98:101], v[82:85], v[74:77]
	v_mfma_f32_16x16x32_bf16 v[58:61], v[98:101], v[90:93], v[58:61]
	ds_read2_b64 v[98:101], v102 offset0:96 offset1:100
	s_waitcnt lgkmcnt(0)
	v_mfma_f32_16x16x32_bf16 v[62:65], v[98:101], v[94:97], v[62:65]
	ds_read2_b64 v[94:97], v102 offset0:104 offset1:108
	s_waitcnt vmcnt(1)
	ds_write_b128 v199, v[38:41] offset:13312
	v_mfma_f32_16x16x32_bf16 v[78:81], v[98:101], v[86:89], v[78:81]
	s_waitcnt lgkmcnt(1)
	v_mfma_f32_16x16x32_bf16 v[86:89], v[94:97], v[82:85], v[78:81]
	v_mfma_f32_16x16x32_bf16 v[62:65], v[94:97], v[90:93], v[62:65]
	s_and_saveexec_b64 s[0:1], s[40:41]
	ds_write_b128 v200, v[42:45] offset:13312
	s_or_b64 exec, exec, s[0:1]
	s_waitcnt vmcnt(0)
	ds_write_b128 v201, v[46:49] offset:35840
	s_waitcnt lgkmcnt(0)
	s_barrier
	v_cndmask_b32_e64 v78, 0, 1, s[52:53]
	v_cmp_ne_u32_e64 s[0:1], 1, v78
	s_andn2_b64 vcc, exec, s[52:53]
	s_cbranch_vccnz .LBB0_622
	global_load_dwordx4 v[38:41], v[116:117], off
	s_and_saveexec_b64 s[48:49], s[40:41]
	s_cbranch_execz .LBB0_621
	global_load_dwordx4 v[42:45], v[118:119], off

; DEV f32x4 mfma16(bf16x8 a, bf16x8 b, f32x4 c) { return __builtin_amdgcn_mfma_f32_16x16x32_bf16(a, b, c, 0, 0, 0); }
; template <int KS>
; DEV void attn_chunk(const unsigned char* Kl, const unsigned char* Vl, const bf16x8 (&qf)[2][KS], f32x4 (&O)[2][4], float (&mrun)[2], float (&lrun)[2],
;                     bool masked, int key0, int qw0, float sl2, int lane, int fr, int fq) {
;     ...
; #pragma unroll
;   for (int kt = 0; kt < 4; ++kt) {
;     sc[0][kt] = (f32x4){0.f, 0.f, 0.f, 0.f}; sc[1][kt] = (f32x4){0.f, 0.f, 0.f, 0.f};
; #pragma unroll
;     for (int kk = 0; kk < KS; ++kk) {
;       bf16x8 kf = *reinterpret_cast<const bf16x8*>(Kl + ((kt * 16 + fr) * KP + kk * 32 + fq * 8) * 2);
;       sc[0][kt] = mfma16(kf, qf[0][kk], sc[0][kt]); sc[1][kt] = mfma16(kf, qf[1][kk], sc[1][kt]);
;     }
;   }
;   bf16x8 pf[2][2];
; #pragma unroll
;   for (int qi = 0; qi < 2; ++qi) {
;     float mx = -1e30f;
; #pragma unroll
;     for (int kt = 0; kt < 4; ++kt)
; #pragma unroll
;       for (int r = 0; r < 4; ++r) { float v = sc[qi][kt][r] * sl2;
;         if (masked) { int kp = key0 + kt * 16 + fq * 4 + r; int dq = qw0 + qi * 16 + fr - kp; if (dq > 128 || dq < -128) v = -1e30f; }
;         sc[qi][kt][r] = v; mx = fmaxf(mx, v); }
;     mx = max_x16_x32(mx);
;     const float mnew = fmaxf(mrun[qi], mx);
;     const float alpha = __builtin_amdgcn_exp2f(mrun[qi] - mnew);
;     mrun[qi] = mnew;
;     float ps = 0.f;
; #pragma unroll
;     for (int kt = 0; kt < 4; ++kt)
; #pragma unroll
;       for (int r = 0; r < 4; ++r) { float pvv = __builtin_amdgcn_exp2f(sc[qi][kt][r] - mnew); ps += pvv; sc[qi][kt][r] = pvv; }
;     pf[qi][0] = pack8(sc[qi][0][0], sc[qi][0][1], sc[qi][0][2], sc[qi][0][3], sc[qi][1][0], sc[qi][1][1], sc[qi][1][2], sc[qi][1][3]);
;     pf[qi][1] = pack8(sc[qi][2][0], sc[qi][2][1], sc[qi][2][2], sc[qi][2][3], sc[qi][3][0], sc[qi][3][1], sc[qi][3][2], sc[qi][3][3]);
;     lrun[qi] = lrun[qi] * alpha + ps;
; #pragma unroll
;     for (int dt = 0; dt < 4; ++dt) O[qi][dt] *= alpha;
;   }
.LBB0_622:
	ds_read_b128 v[78:81], v202 offset:13312
	ds_read_b128 v[90:93], v202 offset:13376
	s_mov_b32 s44, 0xf149f2ca
	s_mov_b32 s8, 0x3e16c740
	s_and_b64 vcc, exec, s[0:1]
	s_waitcnt lgkmcnt(1)
	v_mfma_f32_16x16x32_bf16 v[82:85], v[78:81], v[2:5], 0
	ds_read_b128 v[98:101], v202 offset:16704
	ds_read_b128 v[102:105], v202 offset:20032
	ds_read_b128 v[158:161], v202 offset:23360
	v_mfma_f32_16x16x32_bf16 v[78:81], v[78:81], v[18:21], 0
	s_waitcnt lgkmcnt(3)
	v_mfma_f32_16x16x32_bf16 v[82:85], v[90:93], v[6:9], v[82:85]
	v_mfma_f32_16x16x32_bf16 v[78:81], v[90:93], v[14:17], v[78:81]
	ds_read_b128 v[90:93], v202 offset:13440
	s_waitcnt lgkmcnt(0)
	v_mfma_f32_16x16x32_bf16 v[82:85], v[90:93], v[10:13], v[82:85]
	v_mfma_f32_16x16x32_bf16 v[90:93], v[90:93], v[22:25], v[78:81]
	s_nop 3
	ds_read_b128 v[78:81], v202 offset:16640
	s_waitcnt lgkmcnt(0)
	v_mfma_f32_16x16x32_bf16 v[94:97], v[78:81], v[2:5], 0
	s_nop 0
	v_mfma_f32_16x16x32_bf16 v[78:81], v[78:81], v[18:21], 0
	v_mfma_f32_16x16x32_bf16 v[94:97], v[98:101], v[6:9], v[94:97]
	v_mfma_f32_16x16x32_bf16 v[78:81], v[98:101], v[14:17], v[78:81]
	ds_read_b128 v[98:101], v202 offset:16768
	s_waitcnt lgkmcnt(0)
	v_mfma_f32_16x16x32_bf16 v[166:169], v[98:101], v[10:13], v[94:97]
	v_mfma_f32_16x16x32_bf16 v[94:97], v[98:101], v[22:25], v[78:81]
	s_nop 3
	ds_read_b128 v[78:81], v202 offset:19968
	s_waitcnt lgkmcnt(0)
	v_mfma_f32_16x16x32_bf16 v[98:101], v[78:81], v[2:5], 0
	v_mfma_f32_16x16x32_bf16 v[78:81], v[78:81], v[18:21], 0
	v_mfma_f32_16x16x32_bf16 v[98:101], v[102:105], v[6:9], v[98:101]
	v_mfma_f32_16x16x32_bf16 v[78:81], v[102:105], v[14:17], v[78:81]
	ds_read_b128 v[102:105], v202 offset:20096
	s_waitcnt lgkmcnt(0)
	v_mfma_f32_16x16x32_bf16 v[174:177], v[102:105], v[10:13], v[98:101]
	v_mfma_f32_16x16x32_bf16 v[98:101], v[102:105], v[22:25], v[78:81]
	s_nop 3
	ds_read_b128 v[78:81], v202 offset:23296
	s_waitcnt lgkmcnt(0)
	v_mfma_f32_16x16x32_bf16 v[102:105], v[78:81], v[2:5], 0
	v_mfma_f32_16x16x32_bf16 v[78:81], v[78:81], v[18:21], 0
	v_mfma_f32_16x16x32_bf16 v[102:105], v[158:161], v[6:9], v[102:105]
	v_mfma_f32_16x16x32_bf16 v[78:81], v[158:161], v[14:17], v[78:81]
	ds_read_b128 v[158:161], v202 offset:23424
	s_waitcnt lgkmcnt(0)
	v_mfma_f32_16x16x32_bf16 v[188:191], v[158:161], v[10:13], v[102:105]
	v_mfma_f32_16x16x32_bf16 v[102:105], v[158:161], v[22:25], v[78:81]
	v_max3_f32 v159, v90, s44, v91
	s_nop 0
	s_nop 5
	v_max3_f32 v78, v82, s44, v83
	v_max3_f32 v78, v78, v84, v85
	v_max3_f32 v78, v78, v166, v167
	v_max3_f32 v78, v78, v168, v169
	v_max3_f32 v78, v78, v174, v175
	v_max3_f32 v78, v78, v176, v177
	v_max3_f32 v78, v78, v188, v189
	v_max3_f32 v78, v78, v190, v191
	v_mul_f32_e32 v78, 0x3e16c740, v78
	v_mov_b32_e32 v79, v78
	s_nop 1
	v_permlane32_swap_b32_e32 v78, v79
	v_max_f32_e32 v79, v79, v79
	v_max_f32_e32 v78, v78, v78
	v_max_f32_e32 v78, v78, v79
	v_mov_b32_e32 v79, v78
	s_nop 1
	v_permlane16_swap_b32_e32 v78, v79
	v_max3_f32 v218, v156, v78, v79
	v_max3_f32 v159, v159, v92, v93
	v_fma_f32 v79, v82, s8, -v218
	v_max3_f32 v159, v159, v94, v95
	v_sub_f32_e32 v78, v156, v218
	v_exp_f32_e32 v156, v79
	v_fma_f32 v79, v83, s8, -v218
	v_max3_f32 v159, v159, v96, v97
	v_exp_f32_e32 v160, v79
	v_fma_f32 v79, v84, s8, -v218
	v_max3_f32 v159, v159, v98, v99
	v_exp_f32_e32 v158, v79
	v_fma_f32 v79, v85, s8, -v218
	v_max3_f32 v159, v159, v100, v101
	v_exp_f32_e32 v162, v79
	v_fma_f32 v79, v166, s8, -v218
	v_max3_f32 v159, v159, v102, v103
	v_exp_f32_e32 v166, v79
	v_fma_f32 v79, v167, s8, -v218
	v_max3_f32 v159, v159, v104, v105
	v_exp_f32_e32 v164, v79
	v_fma_f32 v79, v168, s8, -v218
	v_mul_f32_e32 v159, 0x3e16c740, v159
	v_mov_b32_e32 v161, v159
	v_exp_f32_e32 v168, v79
	v_fma_f32 v79, v169, s8, -v218
	v_permlane32_swap_b32_e32 v159, v161
	v_exp_f32_e32 v172, v79
	v_fma_f32 v79, v174, s8, -v218
	v_max_f32_e32 v161, v161, v161
	v_max_f32_e32 v159, v159, v159
	v_exp_f32_e32 v170, v79
	v_fma_f32 v79, v175, s8, -v218
	v_max_f32_e32 v159, v159, v161
	v_exp_f32_e32 v174, v79
	v_fma_f32 v79, v176, s8, -v218
	v_exp_f32_e32 v176, v78
	v_mov_b32_e32 v161, v159
	s_nop 1
	v_permlane16_swap_b32_e32 v159, v161
	v_max3_f32 v219, v157, v159, v161
	v_fma_f32 v90, v90, s8, -v219
	v_exp_f32_e32 v186, v79
	v_fma_f32 v79, v177, s8, -v218
	v_pk_mul_f32 v[68:69], v[68:69], v[176:177] op_sel_hi:[1,0]
	v_pk_mul_f32 v[66:67], v[66:67], v[176:177] op_sel_hi:[1,0]
	v_pk_mul_f32 v[72:73], v[72:73], v[176:177] op_sel_hi:[1,0]
	v_pk_mul_f32 v[70:71], v[70:71], v[176:177] op_sel_hi:[1,0]
	v_pk_mul_f32 v[76:77], v[76:77], v[176:177] op_sel_hi:[1,0]
	v_pk_mul_f32 v[74:75], v[74:75], v[176:177] op_sel_hi:[1,0]
	v_pk_mul_f32 v[88:89], v[88:89], v[176:177] op_sel_hi:[1,0]
	v_pk_mul_f32 v[86:87], v[86:87], v[176:177] op_sel_hi:[1,0]
	v_sub_f32_e32 v177, v157, v219
	v_exp_f32_e32 v157, v90
	v_fma_f32 v90, v91, s8, -v219
	v_exp_f32_e32 v161, v90
	v_fma_f32 v90, v92, s8, -v219
	v_exp_f32_e32 v159, v90
	v_fma_f32 v90, v93, s8, -v219
	v_exp_f32_e32 v163, v90
	v_fma_f32 v90, v94, s8, -v219
	v_exp_f32_e32 v167, v90
	v_fma_f32 v90, v95, s8, -v219
	v_exp_f32_e32 v165, v90
	v_fma_f32 v90, v96, s8, -v219
	v_exp_f32_e32 v169, v90
	v_fma_f32 v90, v97, s8, -v219
	v_exp_f32_e32 v173, v90
	v_fma_f32 v90, v98, s8, -v219
	v_exp_f32_e32 v177, v177
	v_exp_f32_e32 v171, v90
	v_fma_f32 v90, v99, s8, -v219
	v_exp_f32_e32 v175, v90
	v_fma_f32 v90, v100, s8, -v219
	v_exp_f32_e32 v187, v90
	v_fma_f32 v90, v101, s8, -v219
	v_exp_f32_e32 v185, v90
	v_fma_f32 v90, v102, s8, -v219
	v_mov_b32_e32 v98, v177
	v_add_u32_e32 v102, 0x8800, v203
	v_pk_mul_f32 v[52:53], v[52:53], v[98:99] op_sel_hi:[1,0]
	v_pk_mul_f32 v[50:51], v[50:51], v[98:99] op_sel_hi:[1,0]
	v_pk_mul_f32 v[56:57], v[56:57], v[98:99] op_sel_hi:[1,0]
	v_pk_mul_f32 v[54:55], v[54:55], v[98:99] op_sel_hi:[1,0]
	v_pk_mul_f32 v[60:61], v[60:61], v[98:99] op_sel_hi:[1,0]
	v_pk_mul_f32 v[58:59], v[58:59], v[98:99] op_sel_hi:[1,0]
	v_pk_mul_f32 v[64:65], v[64:65], v[98:99] op_sel_hi:[1,0]
	v_pk_mul_f32 v[62:63], v[62:63], v[98:99] op_sel_hi:[1,0]
	ds_read2_b64 v[98:101], v102 offset0:128 offset1:132
	v_cvt_pk_bf16_f32 v82, v156, v160
	v_cvt_pk_bf16_f32 v83, v158, v162
	v_cvt_pk_bf16_f32 v84, v166, v164
	v_cvt_pk_bf16_f32 v85, v168, v172
	v_cvt_pk_bf16_f32 v94, v157, v161
	v_cvt_pk_bf16_f32 v95, v159, v163
	v_cvt_pk_bf16_f32 v96, v167, v165
	v_cvt_pk_bf16_f32 v97, v169, v173
	v_exp_f32_e32 v184, v79
	v_fma_f32 v79, v188, s8, -v218
	s_waitcnt lgkmcnt(0)
; DEV f32x4 mfma16(bf16x8 a, bf16x8 b, f32x4 c) { return __builtin_amdgcn_mfma_f32_16x16x32_bf16(a, b, c, 0, 0, 0); }
; template <int KS>
; DEV void attn_chunk(const unsigned char* Kl, const unsigned char* Vl, const bf16x8 (&qf)[2][KS], f32x4 (&O)[2][4], float (&mrun)[2], float (&lrun)[2],
;                     bool masked, int key0, int qw0, float sl2, int lane, int fr, int fq) {
;     ...
; #pragma unroll
;   for (int dt = 0; dt < 4; ++dt)
; #pragma unroll
;     for (int sub = 0; sub < 2; ++sub) {
;       const unsigned char* vp = Vl + ((dt * 16 + fr) * VP + sub * 32 + fq * 4) * 2;
;       u32x2 v0 = *reinterpret_cast<const u32x2*>(vp), v1 = *reinterpret_cast<const u32x2*>(vp + 32);
;       u32x4 vv = {v0[0], v0[1], v1[0], v1[1]};
;       bf16x8 vf = *reinterpret_cast<bf16x8*>(&vv);
;       O[0][dt] = mfma16(vf, pf[0][sub], O[0][dt]); O[1][dt] = mfma16(vf, pf[1][sub], O[1][dt]);
;     }
	v_mfma_f32_16x16x32_bf16 v[66:69], v[98:101], v[82:85], v[66:69]
	v_exp_f32_e32 v194, v79
	v_fma_f32 v79, v189, s8, -v218
	v_exp_f32_e32 v195, v90
	v_mfma_f32_16x16x32_bf16 v[50:53], v[98:101], v[94:97], v[50:53]
	ds_read2_b64 v[98:101], v102 offset0:136 offset1:140
	v_fma_f32 v90, v103, s8, -v219
	v_exp_f32_e32 v192, v79
	v_fma_f32 v79, v190, s8, -v218
	v_exp_f32_e32 v193, v90
	v_fma_f32 v90, v104, s8, -v219
	v_exp_f32_e32 v190, v79
	v_fma_f32 v79, v191, s8, -v218
	v_exp_f32_e32 v191, v90
	v_fma_f32 v90, v105, s8, -v219
	v_exp_f32_e32 v188, v79
	v_exp_f32_e32 v189, v90
	v_cvt_pk_bf16_f32 v78, v170, v174
	v_cvt_pk_bf16_f32 v79, v186, v184
	v_cvt_pk_bf16_f32 v80, v194, v192
	v_cvt_pk_bf16_f32 v81, v190, v188
	v_cvt_pk_bf16_f32 v90, v171, v175
	v_cvt_pk_bf16_f32 v91, v187, v185
	v_cvt_pk_bf16_f32 v92, v195, v193
	v_cvt_pk_bf16_f32 v93, v191, v189
	v_add_u32_e32 v102, 0x9000, v203
	s_waitcnt lgkmcnt(0)
	v_mfma_f32_16x16x32_bf16 v[66:69], v[98:101], v[78:81], v[66:69]
	v_mfma_f32_16x16x32_bf16 v[50:53], v[98:101], v[90:93], v[50:53]
	ds_read2_b64 v[98:101], v102 offset0:160 offset1:164
	s_waitcnt lgkmcnt(0)
	v_mfma_f32_16x16x32_bf16 v[70:73], v[98:101], v[82:85], v[70:73]
	v_mfma_f32_16x16x32_bf16 v[54:57], v[98:101], v[94:97], v[54:57]
	ds_read2_b64 v[98:101], v102 offset0:168 offset1:172
	v_add_u32_e32 v102, 0x9800, v203
	s_waitcnt lgkmcnt(0)
	v_mfma_f32_16x16x32_bf16 v[70:73], v[98:101], v[78:81], v[70:73]
	v_mfma_f32_16x16x32_bf16 v[54:57], v[98:101], v[90:93], v[54:57]
	ds_read2_b64 v[98:101], v102 offset0:192 offset1:196
	s_waitcnt lgkmcnt(0)
	v_mfma_f32_16x16x32_bf16 v[74:77], v[98:101], v[82:85], v[74:77]
	v_mfma_f32_16x16x32_bf16 v[58:61], v[98:101], v[94:97], v[58:61]
	ds_read2_b64 v[98:101], v102 offset0:200 offset1:204
	v_add_u32_e32 v102, 0xa000, v203
	s_waitcnt lgkmcnt(0)
	v_mfma_f32_16x16x32_bf16 v[74:77], v[98:101], v[78:81], v[74:77]
	v_mfma_f32_16x16x32_bf16 v[58:61], v[98:101], v[90:93], v[58:61]
	ds_read2_b64 v[98:101], v102 offset0:224 offset1:228
	s_waitcnt lgkmcnt(0)
	v_mfma_f32_16x16x32_bf16 v[82:85], v[98:101], v[82:85], v[86:89]
	s_nop 2
	ds_read2_b64 v[86:89], v102 offset0:232 offset1:236
	v_mfma_f32_16x16x32_bf16 v[62:65], v[98:101], v[94:97], v[62:65]
	s_waitcnt lgkmcnt(0)
	v_mfma_f32_16x16x32_bf16 v[78:81], v[86:89], v[78:81], v[82:85]
	v_mfma_f32_16x16x32_bf16 v[62:65], v[86:89], v[90:93], v[62:65]
	s_cbranch_vccnz .LBB0_611
	ds_write_b128 v199, v[26:29]
	s_and_saveexec_b64 s[0:1], s[40:41]
	s_cbranch_execz .LBB0_610
	ds_write_b128 v200, v[30:33]
	s_branch .LBB0_610
